# packed fp32 ops split into single ops in the ctx-scan step too (bit-identical)
# speedup vs baseline: 1.0067x; 1.0030x over previous
.LBB0_254:
	v_add_u32_e32 v3, 0xb000, v207
	ds_read_b128 v[56:59], v206 offset:45056
	ds_read2_b32 v[166:167], v3 offset1:16
	ds_read_b128 v[52:55], v206 offset:45120
	ds_read_b128 v[48:51], v206 offset:45184
	ds_read2_b32 v[160:161], v3 offset0:32 offset1:48
	ds_read_b128 v[44:47], v206 offset:45248
	ds_read_b32 v222, v2 offset:45308
	ds_read_b128 v[74:77], v210 offset:27648
	ds_read_b128 v[78:81], v210 offset:28672
	v_cvt_pk_bf16_f32 v64, v40, v41
	v_cvt_pk_bf16_f32 v65, v42, v43
	v_cvt_pk_bf16_f32 v66, v36, v37
	v_cvt_pk_bf16_f32 v67, v38, v39
	v_cvt_pk_bf16_f32 v60, v32, v33
	v_cvt_pk_bf16_f32 v61, v34, v35
	s_waitcnt lgkmcnt(1)
	v_mfma_f32_16x16x32_bf16 v[74:77], v[74:77], v[64:67], 0
	v_cvt_pk_bf16_f32 v62, v28, v29
	v_cvt_pk_bf16_f32 v63, v30, v31
	s_mov_b32 s0, 0x5040100
	v_readlane_b32 s84, v254, 26
	s_waitcnt lgkmcnt(0)
	v_mfma_f32_16x16x32_bf16 v[74:77], v[78:81], v[60:63], v[74:77]
	s_waitcnt vmcnt(13)
	v_lshlrev_b32_e32 v78, 16, v72
	v_and_b32_e32 v79, 0xffff0000, v72
	v_lshlrev_b32_e32 v72, 16, v73
	v_and_b32_e32 v73, 0xffff0000, v73
	v_readlane_b32 s86, v254, 28
	s_nop 1
	v_sub_f32_e32 v158, v78, v74
	v_sub_f32_e32 v159, v79, v75
	v_sub_f32_e32 v156, v72, v76
	v_sub_f32_e32 v157, v73, v77
	ds_read_b128 v[72:75], v210 offset:29696
	ds_read_b128 v[76:79], v210 offset:30720
	s_waitcnt lgkmcnt(1)
	v_mfma_f32_16x16x32_bf16 v[72:75], v[72:75], v[64:67], 0
	v_readlane_b32 s87, v254, 29
	v_readlane_b32 s85, v254, 27
	v_add_u32_e32 v191, v215, v213
	s_waitcnt lgkmcnt(0)
	v_mfma_f32_16x16x32_bf16 v[72:75], v[76:79], v[60:63], v[72:75]
	s_waitcnt vmcnt(12)
	v_lshlrev_b32_e32 v76, 16, v70
	v_and_b32_e32 v77, 0xffff0000, v70
	v_lshlrev_b32_e32 v70, 16, v71
	v_and_b32_e32 v71, 0xffff0000, v71
	v_mov_b64_e32 v[110:111], s[86:87]
	s_nop 1
	v_sub_f32_e32 v154, v76, v72
	v_sub_f32_e32 v155, v77, v73
	v_sub_f32_e32 v150, v70, v74
	v_sub_f32_e32 v151, v71, v75
	ds_read_b128 v[70:73], v210 offset:31744
	ds_read_b128 v[74:77], v210 offset:32768
	s_waitcnt lgkmcnt(1)
	v_mfma_f32_16x16x32_bf16 v[70:73], v[70:73], v[64:67], 0
	v_mov_b64_e32 v[108:109], s[84:85]
	s_add_i32 s92, s92, 1
	s_mov_b64 s[80:81], 0
	s_waitcnt lgkmcnt(0)
	v_mfma_f32_16x16x32_bf16 v[70:73], v[74:77], v[60:63], v[70:73]
	s_waitcnt vmcnt(11)
	v_lshlrev_b32_e32 v74, 16, v68
	v_and_b32_e32 v75, 0xffff0000, v68
	v_lshlrev_b32_e32 v68, 16, v69
	v_and_b32_e32 v69, 0xffff0000, v69
	s_mov_b32 s20, s82
	s_nop 1
	v_sub_f32_e32 v152, v74, v70
	v_sub_f32_e32 v153, v75, v71
	v_sub_f32_e32 v148, v68, v72
	v_sub_f32_e32 v149, v69, v73
	ds_read_b128 v[68:71], v210 offset:33792
	ds_read_b128 v[72:75], v210 offset:34816
	s_waitcnt lgkmcnt(1)
	v_mfma_f32_16x16x32_bf16 v[68:71], v[68:71], v[64:67], 0
	s_waitcnt lgkmcnt(0)
	v_mfma_f32_16x16x32_bf16 v[68:71], v[72:75], v[60:63], v[68:71]
	s_waitcnt vmcnt(10)
	v_lshlrev_b32_e32 v72, 16, v0
	v_and_b32_e32 v73, 0xffff0000, v0
	v_lshlrev_b32_e32 v0, 16, v1
	v_and_b32_e32 v1, 0xffff0000, v1
	v_cvt_pk_bf16_f32 v74, v154, v155
	s_nop 1
	v_sub_f32_e32 v162, v0, v70
	v_sub_f32_e32 v163, v1, v71
	v_add_u32_e32 v0, v206, v211
	ds_read_b128 v[100:103], v0 offset:9216
	ds_read_b128 v[104:107], v0 offset:9280
	ds_read_b128 v[92:95], v0 offset:11520
	ds_read_b128 v[96:99], v0 offset:11584
	ds_read_b128 v[84:87], v0 offset:13824
	ds_read_b128 v[88:91], v0 offset:13888
	ds_read_b128 v[76:79], v0 offset:16128
	ds_read_b128 v[80:83], v0 offset:16192
	ds_read_b128 v[224:227], v212 offset:64
	ds_read_b128 v[228:231], v212
	s_waitcnt lgkmcnt(0)
	v_mfma_f32_16x16x32_bf16 v[228:231], v[100:103], v[228:231], 0
	v_sub_f32_e32 v0, v166, v56
	v_mul_f32_e32 v0, 0x3fb8aa3b, v0
	v_exp_f32_e32 v0, v0
	v_mfma_f32_16x16x32_bf16 v[224:227], v[104:107], v[224:227], v[228:231]
	v_sub_f32_e32 v1, v166, v59
	v_mul_f32_e32 v1, 0x3fb8aa3b, v1
	v_exp_f32_e32 v1, v1
	v_sub_f32_e32 v164, v72, v68
	v_sub_f32_e32 v165, v73, v69
	v_cvt_pk_bf16_f32 v72, v158, v159
	s_nop 2
	v_mul_f32_e32 v0, v0, v224
	v_cndmask_b32_e64 v3, v0, 0, s[40:41]
	v_sub_f32_e32 v0, v166, v57
	v_mul_f32_e32 v0, 0x3fb8aa3b, v0
	v_exp_f32_e32 v0, v0
	v_cvt_pk_bf16_f32 v73, v156, v157
	v_cvt_pk_bf16_f32 v75, v150, v151
	v_cvt_pk_bf16_f32 v68, v152, v153
	v_mul_f32_e32 v0, v0, v225
	v_cndmask_b32_e64 v190, 0, v0, s[42:43]
	v_sub_f32_e32 v0, v166, v58
	v_mul_f32_e32 v0, 0x3fb8aa3b, v0
	v_exp_f32_e32 v0, v0
	v_add_u32_e32 v166, v212, v213
	ds_read2_b64 v[232:235], v166 offset0:8 offset1:12
	v_cvt_pk_bf16_f32 v69, v148, v149
	v_mul_f32_e32 v188, v0, v226
	v_mul_f32_e32 v189, v1, v227
	ds_read2_b64 v[224:227], v166 offset1:4
	v_cvt_pk_bf16_f32 v1, v188, v189
	v_cvt_pk_bf16_f32 v0, v3, v190
	v_cndmask_b32_e64 v3, v1, 0, s[46:47]
	v_lshrrev_b32_e32 v1, 16, v1
	v_cndmask_b32_e64 v1, v1, 0, s[44:45]
	v_perm_b32 v1, v1, v3, s0
	v_mov_b32_e32 v3, v2
	s_waitcnt lgkmcnt(0)
	v_mfma_f32_16x16x32_bf16 v[224:227], v[224:227], v[64:67], 0
	v_cvt_pk_bf16_f32 v70, v164, v165
	v_cvt_pk_bf16_f32 v71, v162, v163
	v_sub_f32_e32 v166, v167, v53
	v_mfma_f32_16x16x32_bf16 v[228:231], v[0:3], v[72:75], 0
	v_mul_f32_e32 v0, 0x3fb8aa3b, v56
	v_exp_f32_e32 v0, v0
	v_mul_f32_e32 v166, 0x3fb8aa3b, v166
	v_mfma_f32_16x16x32_bf16 v[224:227], v[232:235], v[60:63], v[224:227]
	v_exp_f32_e32 v166, v166
	v_sub_f32_e32 v3, v167, v58
	v_mul_f32_e32 v3, 0x3fb8aa3b, v3
	v_mfma_f32_16x16x32_bf16 v[228:231], v[108:111], v[68:71], v[228:231]
	v_exp_f32_e32 v188, v3
	v_sub_f32_e32 v3, v167, v59
	v_mul_f32_e32 v3, 0x3fb8aa3b, v3
	v_sub_f32_e32 v1, v167, v57
	v_exp_f32_e32 v189, v3
	s_nop 2
	v_fma_f32 v0, v0, v224, v228
	v_cvt_pk_bf16_f32 v0, v0, s0
	ds_write_b16 v214, v0 offset:35840
	v_mul_f32_e32 v0, 0x3fb8aa3b, v57
	v_exp_f32_e32 v0, v0
	v_sub_f32_e32 v3, v167, v52
	v_mul_f32_e32 v1, 0x3fb8aa3b, v1
	v_mul_f32_e32 v3, 0x3fb8aa3b, v3
	v_fma_f32 v0, v0, v225, v229
	v_cvt_pk_bf16_f32 v0, v0, s0
	ds_write_b16 v214, v0 offset:35984
	v_mul_f32_e32 v0, 0x3fb8aa3b, v58
	v_exp_f32_e32 v0, v0
	v_exp_f32_e32 v1, v1
	v_exp_f32_e32 v3, v3
	v_fma_f32 v0, v0, v226, v230
	v_cvt_pk_bf16_f32 v0, v0, s0
	ds_write_b16 v214, v0 offset:36128
	v_mul_f32_e32 v0, 0x3fb8aa3b, v59
	v_exp_f32_e32 v0, v0
	s_nop 0
	v_fmac_f32_e32 v231, v0, v227
	v_cvt_pk_bf16_f32 v0, v231, s0
	ds_write_b16 v214, v0 offset:36272
	ds_read_b128 v[224:227], v215
	ds_read_b128 v[228:231], v215 offset:64
	s_waitcnt lgkmcnt(1)
	v_mfma_f32_16x16x32_bf16 v[232:235], v[100:103], v[224:227], 0
	v_sub_f32_e32 v0, v167, v56
	v_mul_f32_e32 v0, 0x3fb8aa3b, v0
	v_exp_f32_e32 v0, v0
	v_mfma_f32_16x16x32_bf16 v[224:227], v[92:95], v[224:227], 0
	s_waitcnt lgkmcnt(0)
	v_mfma_f32_16x16x32_bf16 v[224:227], v[96:99], v[228:231], v[224:227]
	v_mfma_f32_16x16x32_bf16 v[232:235], v[104:107], v[228:231], v[232:235]
	s_nop 6
	v_mul_f32_e32 v166, v166, v225
	v_cndmask_b32_e64 v190, v166, 0, s[48:49]
	v_sub_f32_e32 v166, v167, v54
	v_sub_f32_e32 v167, v167, v55
	v_mul_f32_e32 v166, 0x3fb8aa3b, v166
	v_mul_f32_e32 v167, 0x3fb8aa3b, v167
	v_exp_f32_e32 v166, v166
	v_exp_f32_e32 v167, v167
	v_mul_f32_e32 v0, v0, v232
	v_mul_f32_e32 v1, v1, v233
	v_mul_f32_e32 v3, v3, v224
	v_cvt_pk_bf16_f32 v228, v0, v1
	v_mul_f32_e32 v166, v166, v226
	v_mul_f32_e32 v167, v167, v227
	ds_read2_b64 v[224:227], v191 offset1:4
	v_cvt_pk_bf16_f32 v0, v166, v167
	v_cndmask_b32_e64 v1, v0, 0, s[52:53]
	v_lshrrev_b32_e32 v0, 16, v0
	v_mul_f32_e32 v188, v188, v234
	v_mul_f32_e32 v189, v189, v235
	v_cndmask_b32_e64 v3, v3, 0, s[40:41]
	v_cndmask_b32_e64 v0, v0, 0, s[50:51]
	v_cvt_pk_bf16_f32 v229, v188, v189
	v_cvt_pk_bf16_f32 v230, v3, v190
	v_perm_b32 v231, v0, v1, s0
	ds_read2_b64 v[232:235], v191 offset0:8 offset1:12
	s_waitcnt lgkmcnt(1)
	v_mfma_f32_16x16x32_bf16 v[224:227], v[224:227], v[64:67], 0
	v_mul_f32_e32 v0, 0x3fb8aa3b, v52
	v_exp_f32_e32 v0, v0
	v_sub_f32_e32 v3, v160, v58
	v_mfma_f32_16x16x32_bf16 v[228:231], v[228:231], v[72:75], 0
	v_mul_f32_e32 v3, 0x3fb8aa3b, v3
	v_exp_f32_e32 v166, v3
	v_sub_f32_e32 v3, v160, v59
	s_waitcnt lgkmcnt(0)
	v_mfma_f32_16x16x32_bf16 v[224:227], v[232:235], v[60:63], v[224:227]
	v_mul_f32_e32 v3, 0x3fb8aa3b, v3
	v_sub_f32_e32 v1, v160, v57
	v_exp_f32_e32 v167, v3
	v_mfma_f32_16x16x32_bf16 v[108:111], v[108:111], v[68:71], v[228:231]
	v_sub_f32_e32 v3, v160, v52
	v_mul_f32_e32 v1, 0x3fb8aa3b, v1
	v_mul_f32_e32 v3, 0x3fb8aa3b, v3
	v_exp_f32_e32 v1, v1
	v_exp_f32_e32 v188, v3
	s_nop 2
	v_fma_f32 v0, v0, v224, v108
	v_cvt_pk_bf16_f32 v0, v0, s0
	ds_write_b16 v214, v0 offset:38144
	v_mul_f32_e32 v0, 0x3fb8aa3b, v53
	v_exp_f32_e32 v0, v0
	v_sub_f32_e32 v3, v160, v53
	v_mul_f32_e32 v3, 0x3fb8aa3b, v3
	v_exp_f32_e32 v189, v3
	v_fma_f32 v0, v0, v225, v109
	v_cvt_pk_bf16_f32 v0, v0, s0
	ds_write_b16 v214, v0 offset:38288
	v_mul_f32_e32 v0, 0x3fb8aa3b, v54
	v_exp_f32_e32 v0, v0
	v_sub_f32_e32 v3, v160, v54
	v_mul_f32_e32 v3, 0x3fb8aa3b, v3
	v_exp_f32_e32 v190, v3
	v_fma_f32 v0, v0, v226, v110
	v_cvt_pk_bf16_f32 v0, v0, s0
	ds_write_b16 v214, v0 offset:38432
	v_mul_f32_e32 v0, 0x3fb8aa3b, v55
	v_exp_f32_e32 v0, v0
	v_sub_f32_e32 v3, v160, v55
	v_mul_f32_e32 v3, 0x3fb8aa3b, v3
	v_exp_f32_e32 v191, v3
	v_fmac_f32_e32 v111, v0, v227
	v_cvt_pk_bf16_f32 v0, v111, s0
	ds_write_b16 v214, v0 offset:38576
	ds_read_b128 v[108:111], v216
	ds_read_b128 v[224:227], v216 offset:64
	s_waitcnt lgkmcnt(1)
	v_mfma_f32_16x16x32_bf16 v[228:231], v[100:103], v[108:111], 0
	v_sub_f32_e32 v0, v160, v56
	v_mul_f32_e32 v0, 0x3fb8aa3b, v0
	v_exp_f32_e32 v0, v0
	s_waitcnt lgkmcnt(0)
	v_mfma_f32_16x16x32_bf16 v[228:231], v[104:107], v[224:227], v[228:231]
	v_sub_f32_e32 v3, v160, v48
	v_mul_f32_e32 v3, 0x3fb8aa3b, v3
	v_exp_f32_e32 v3, v3
	s_nop 4
	v_mul_f32_e32 v0, v0, v228
	v_mul_f32_e32 v1, v1, v229
	v_mul_f32_e32 v166, v166, v230
	v_mul_f32_e32 v167, v167, v231
	v_mfma_f32_16x16x32_bf16 v[228:231], v[92:95], v[108:111], 0
	v_mfma_f32_16x16x32_bf16 v[108:111], v[84:87], v[108:111], 0
	v_mfma_f32_16x16x32_bf16 v[108:111], v[88:91], v[224:227], v[108:111]
	v_mfma_f32_16x16x32_bf16 v[228:231], v[96:99], v[224:227], v[228:231]
	v_cvt_pk_bf16_f32 v224, v0, v1
	s_nop 5
	v_mul_f32_e32 v3, v3, v108
	v_sub_f32_e32 v108, v160, v49
	v_mul_f32_e32 v108, 0x3fb8aa3b, v108
	v_exp_f32_e32 v108, v108
	v_mul_f32_e32 v188, v188, v228
	v_mul_f32_e32 v189, v189, v229
	v_mul_f32_e32 v190, v190, v230
	v_mul_f32_e32 v191, v191, v231
	v_cvt_pk_bf16_f32 v225, v166, v167
	v_mul_f32_e32 v108, v108, v109
	v_cndmask_b32_e64 v223, v108, 0, s[54:55]
	v_sub_f32_e32 v108, v160, v50
	v_sub_f32_e32 v109, v160, v51
	v_mul_f32_e32 v108, 0x3fb8aa3b, v108
	v_mul_f32_e32 v109, 0x3fb8aa3b, v109
	v_exp_f32_e32 v108, v108
	v_exp_f32_e32 v109, v109
	v_add_u32_e32 v160, v216, v213
	v_cvt_pk_bf16_f32 v226, v188, v189
	v_cvt_pk_bf16_f32 v227, v190, v191
	v_mul_f32_e32 v232, v108, v110
	v_mul_f32_e32 v233, v109, v111
	ds_read2_b64 v[108:111], v160 offset1:4
	v_cndmask_b32_e64 v3, v3, 0, s[40:41]
	ds_read2_b64 v[228:231], v160 offset0:8 offset1:12
	v_cvt_pk_bf16_f32 v1, v232, v233
	v_cvt_pk_bf16_f32 v0, v3, v223
	v_cndmask_b32_e64 v3, v1, 0, s[58:59]
	v_lshrrev_b32_e32 v1, 16, v1
	v_cndmask_b32_e64 v1, v1, 0, s[56:57]
	v_perm_b32 v1, v1, v3, s0
	v_mov_b32_e32 v3, v2
	v_mfma_f32_16x16x32_bf16 v[224:227], v[224:227], v[72:75], 0
	s_waitcnt lgkmcnt(1)
	v_mfma_f32_16x16x32_bf16 v[108:111], v[108:111], v[64:67], 0
	v_mfma_f32_16x16x32_bf16 v[224:227], v[0:3], v[68:71], v[224:227]
	v_mul_f32_e32 v0, 0x3fb8aa3b, v48
	v_exp_f32_e32 v0, v0
	v_sub_f32_e32 v1, v161, v57
	s_waitcnt lgkmcnt(0)
	v_mfma_f32_16x16x32_bf16 v[108:111], v[228:231], v[60:63], v[108:111]
	v_mul_f32_e32 v1, 0x3fb8aa3b, v1
	v_exp_f32_e32 v1, v1
	v_sub_f32_e32 v3, v161, v58
	v_mul_f32_e32 v3, 0x3fb8aa3b, v3
	s_nop 3
	v_fma_f32 v0, v0, v108, v224
	v_cvt_pk_bf16_f32 v0, v0, s0
	ds_write_b16 v214, v0 offset:40448
	v_mul_f32_e32 v0, 0x3fb8aa3b, v49
	v_exp_f32_e32 v0, v0
	s_nop 0
	v_fma_f32 v0, v0, v109, v225
	v_cvt_pk_bf16_f32 v0, v0, s0
	ds_write_b16 v214, v0 offset:40592
	v_mul_f32_e32 v0, 0x3fb8aa3b, v50
	v_exp_f32_e32 v0, v0
	s_nop 0
	v_fma_f32 v0, v0, v110, v226
	v_cvt_pk_bf16_f32 v0, v0, s0
	ds_write_b16 v214, v0 offset:40736
	v_mul_f32_e32 v0, 0x3fb8aa3b, v51
	v_exp_f32_e32 v0, v0
	s_nop 0
	v_fmac_f32_e32 v227, v0, v111
	v_cvt_pk_bf16_f32 v0, v227, s0
	ds_write_b16 v214, v0 offset:40880
	ds_read_b128 v[108:111], v217
	ds_read_b128 v[224:227], v217 offset:64
	s_waitcnt lgkmcnt(1)
	v_mfma_f32_16x16x32_bf16 v[100:103], v[100:103], v[108:111], 0
	v_sub_f32_e32 v0, v161, v56
	v_mul_f32_e32 v0, 0x3fb8aa3b, v0
	v_exp_f32_e32 v0, v0
	s_waitcnt lgkmcnt(0)
	v_mfma_f32_16x16x32_bf16 v[100:103], v[104:107], v[224:227], v[100:103]
	v_mfma_f32_16x16x32_bf16 v[92:95], v[92:95], v[108:111], 0
	v_mfma_f32_16x16x32_bf16 v[92:95], v[96:99], v[224:227], v[92:95]
	s_nop 5
	v_mul_f32_e64 v0, v0, v100
	v_mul_f32_e64 v1, v1, v101
	v_exp_f32_e32 v100, v3
	v_sub_f32_e32 v3, v161, v59
	v_mul_f32_e32 v3, 0x3fb8aa3b, v3
	v_exp_f32_e32 v101, v3
	v_sub_f32_e32 v3, v161, v52
	v_mul_f32_e32 v3, 0x3fb8aa3b, v3
	v_exp_f32_e32 v96, v3
	v_sub_f32_e32 v3, v161, v53
	v_mul_f32_e32 v3, 0x3fb8aa3b, v3
	v_exp_f32_e32 v97, v3
	v_sub_f32_e32 v3, v161, v54
	v_mul_f32_e32 v3, 0x3fb8aa3b, v3
	v_mfma_f32_16x16x32_bf16 v[84:87], v[84:87], v[108:111], 0
	v_mul_f32_e64 v92, v96, v92
	v_mul_f32_e64 v93, v97, v93
	v_exp_f32_e32 v96, v3
	v_sub_f32_e32 v3, v161, v55
	v_mul_f32_e32 v3, 0x3fb8aa3b, v3
	v_exp_f32_e32 v97, v3
	v_sub_f32_e32 v3, v161, v48
	v_mul_f32_e32 v3, 0x3fb8aa3b, v3
	v_mfma_f32_16x16x32_bf16 v[84:87], v[88:91], v[224:227], v[84:87]
	v_exp_f32_e32 v88, v3
	v_sub_f32_e32 v3, v161, v49
	v_mul_f32_e32 v3, 0x3fb8aa3b, v3
	v_exp_f32_e32 v89, v3
	v_sub_f32_e32 v3, v161, v50
	v_mul_f32_e32 v3, 0x3fb8aa3b, v3
	v_mfma_f32_16x16x32_bf16 v[76:79], v[76:79], v[108:111], 0
	s_nop 0
	v_mul_f32_e64 v84, v88, v84
	v_mul_f32_e64 v85, v89, v85
	v_exp_f32_e32 v88, v3
	v_sub_f32_e32 v3, v161, v51
	v_mul_f32_e32 v3, 0x3fb8aa3b, v3
	v_exp_f32_e32 v89, v3
	v_sub_f32_e32 v3, v161, v44
	v_mul_f32_e32 v3, 0x3fb8aa3b, v3
	v_mfma_f32_16x16x32_bf16 v[76:79], v[80:83], v[224:227], v[76:79]
	v_exp_f32_e32 v3, v3
	v_add_u32_e32 v83, v217, v213
	v_mul_f32_e32 v100, v100, v102
	v_mul_f32_e32 v101, v101, v103
	v_mul_f32_e32 v94, v96, v94
	v_mul_f32_e32 v95, v97, v95
	v_mul_f32_e32 v86, v88, v86
	v_mul_f32_e32 v87, v89, v87
	s_nop 2
	v_mul_f32_e32 v3, v3, v76
	v_sub_f32_e32 v76, v161, v45
	v_mul_f32_e32 v76, 0x3fb8aa3b, v76
	v_exp_f32_e32 v76, v76
	v_cndmask_b32_e64 v3, v3, 0, s[40:41]
	v_mul_f32_e32 v76, v76, v77
	v_cndmask_b32_e64 v82, v76, 0, s[60:61]
	v_sub_f32_e32 v76, v161, v46
	v_sub_f32_e32 v77, v161, v47
	v_mul_f32_e32 v76, 0x3fb8aa3b, v76
	v_mul_f32_e32 v77, 0x3fb8aa3b, v77
	v_exp_f32_e32 v76, v76
	v_exp_f32_e32 v77, v77
	s_nop 0
	v_mul_f32_e32 v80, v76, v78
	v_mul_f32_e32 v81, v77, v79
	ds_read2_b64 v[76:79], v83 offset1:4
	s_waitcnt lgkmcnt(0)
	v_mfma_f32_16x16x32_bf16 v[64:67], v[76:79], v[64:67], 0
	v_cvt_pk_bf16_f32 v76, v0, v1
	v_cvt_pk_bf16_f32 v77, v100, v101
	v_cvt_pk_bf16_f32 v78, v92, v93
	v_cvt_pk_bf16_f32 v79, v94, v95
	v_cvt_pk_bf16_f32 v0, v80, v81
	v_cndmask_b32_e64 v1, v0, 0, s[64:65]
	v_mfma_f32_16x16x32_bf16 v[72:75], v[76:79], v[72:75], 0
	ds_read2_b64 v[76:79], v83 offset0:8 offset1:12
	v_lshrrev_b32_e32 v0, 16, v0
	v_cndmask_b32_e64 v0, v0, 0, s[62:63]
	s_waitcnt lgkmcnt(0)
	v_mfma_f32_16x16x32_bf16 v[60:63], v[76:79], v[60:63], v[64:67]
	s_nop 2
	v_cvt_pk_bf16_f32 v64, v84, v85
	v_cvt_pk_bf16_f32 v65, v86, v87
	v_cvt_pk_bf16_f32 v66, v3, v82
	v_perm_b32 v67, v0, v1, s0
	v_mul_f32_e32 v0, 0x3fb8aa3b, v44
	v_exp_f32_e32 v0, v0
	v_mfma_f32_16x16x32_bf16 v[64:67], v[64:67], v[68:71], v[72:75]
	v_sub_f32_e32 v3, v222, v58
	v_mul_f32_e32 v3, 0x3fb8aa3b, v3
	v_sub_f32_e32 v1, v222, v57
	s_nop 4
	v_fma_f32 v0, v0, v60, v64
	v_cvt_pk_bf16_f32 v0, v0, s0
	ds_write_b16 v214, v0 offset:42752
	v_mul_f32_e32 v0, 0x3fb8aa3b, v45
	v_exp_f32_e32 v0, v0
	v_mul_f32_e32 v1, 0x3fb8aa3b, v1
	v_exp_f32_e32 v1, v1
	s_waitcnt vmcnt(3)
	v_mov_b64_e32 v[72:73], v[140:141]
	v_fma_f32 v0, v0, v61, v65
	v_cvt_pk_bf16_f32 v0, v0, s0
	ds_write_b16 v218, v0 offset:35840
	v_mul_f32_e32 v0, 0x3fb8aa3b, v46
	v_exp_f32_e32 v0, v0
	s_nop 0
	v_fma_f32 v0, v0, v62, v66
	v_cvt_pk_bf16_f32 v0, v0, s0
	ds_write_b16 v219, v0 offset:35840
	v_mul_f32_e32 v0, 0x3fb8aa3b, v47
	v_exp_f32_e32 v0, v0
	s_nop 0
	v_fmac_f32_e32 v67, v0, v63
	v_cvt_pk_bf16_f32 v0, v67, s0
	ds_write_b16 v220, v0 offset:35840
	v_sub_f32_e32 v0, v222, v56
	v_exp_f32_e32 v56, v3
	v_sub_f32_e32 v3, v222, v59
	v_mul_f32_e32 v3, 0x3fb8aa3b, v3
	v_exp_f32_e32 v57, v3
	v_sub_f32_e32 v3, v222, v52
	v_mul_f32_e32 v3, 0x3fb8aa3b, v3
	v_exp_f32_e32 v52, v3
	v_sub_f32_e32 v3, v222, v53
	v_mul_f32_e32 v3, 0x3fb8aa3b, v3
	v_exp_f32_e32 v53, v3
	v_sub_f32_e32 v3, v222, v54
	v_mul_f32_e32 v3, 0x3fb8aa3b, v3
	v_exp_f32_e32 v54, v3
	v_sub_f32_e32 v3, v222, v55
	v_mul_f32_e32 v3, 0x3fb8aa3b, v3
	v_exp_f32_e32 v55, v3
	v_sub_f32_e32 v3, v222, v48
	v_mul_f32_e32 v3, 0x3fb8aa3b, v3
	v_exp_f32_e32 v48, v3
	v_sub_f32_e32 v3, v222, v49
	v_mul_f32_e32 v3, 0x3fb8aa3b, v3
	v_exp_f32_e32 v49, v3
	v_sub_f32_e32 v3, v222, v50
	v_mul_f32_e32 v3, 0x3fb8aa3b, v3
	v_exp_f32_e32 v50, v3
	v_sub_f32_e32 v3, v222, v51
	v_mul_f32_e32 v3, 0x3fb8aa3b, v3
	v_exp_f32_e32 v51, v3
	v_sub_f32_e32 v3, v222, v44
	v_mul_f32_e32 v3, 0x3fb8aa3b, v3
	v_mul_f32_e32 v0, 0x3fb8aa3b, v0
	v_exp_f32_e32 v44, v3
	v_sub_f32_e32 v3, v222, v45
	v_exp_f32_e32 v0, v0
	v_mul_f32_e32 v3, 0x3fb8aa3b, v3
	v_exp_f32_e32 v45, v3
	v_sub_f32_e32 v3, v222, v46
	v_mul_f32_e32 v3, 0x3fb8aa3b, v3
	v_exp_f32_e32 v46, v3
	v_sub_f32_e32 v3, v222, v47
	v_mul_f32_e32 v0, v0, v158
	v_mul_f32_e32 v1, v1, v159
	v_mul_f32_e32 v3, 0x3fb8aa3b, v3
	v_mul_f32_e32 v58, v56, v156
	v_mul_f32_e32 v59, v57, v157
	v_exp_f32_e32 v47, v3
	v_cvt_pk_bf16_f32 v56, v0, v1
	v_mul_f32_e32 v0, 0x3fb8aa3b, v222
	v_exp_f32_e32 v0, v0
	v_mul_f32_e32 v44, v44, v164
	v_mul_f32_e32 v45, v45, v165
	v_mul_f32_e32 v46, v46, v162
	v_mul_f32_e32 v47, v47, v163
	v_cvt_pk_bf16_f32 v62, v44, v45
	v_cvt_pk_bf16_f32 v63, v46, v47
	v_mul_f32_e32 v46, v42, v0
	v_mul_f32_e32 v47, v43, v0
	v_mul_f32_e32 v44, v40, v0
	v_mul_f32_e32 v45, v41, v0
	v_add_u32_e32 v1, v208, v211
	v_mul_f32_e32 v48, v48, v152
	v_mul_f32_e32 v49, v49, v153
	v_mul_f32_e32 v50, v50, v148
	v_mul_f32_e32 v51, v51, v149
	v_add_u32_e32 v3, 0x4800, v1
	v_cvt_pk_bf16_f32 v60, v48, v49
	v_cvt_pk_bf16_f32 v61, v50, v51
	ds_read2_b64 v[48:51], v3 offset1:4
	v_mul_f32_e32 v52, v52, v154
	v_mul_f32_e32 v53, v53, v155
	v_mul_f32_e32 v54, v54, v150
	v_mul_f32_e32 v55, v55, v151
	v_cvt_pk_bf16_f32 v57, v58, v59
	v_cvt_pk_bf16_f32 v58, v52, v53
	v_cvt_pk_bf16_f32 v59, v54, v55
	s_waitcnt lgkmcnt(0)
	s_nop 0
	v_mfma_f32_16x16x32_bf16 v[44:47], v[48:51], v[56:59], v[44:47]
	ds_read2_b64 v[48:51], v3 offset0:8 offset1:12
	v_add_u32_e32 v3, 0x5000, v1
	ds_read2_b64 v[52:55], v3 offset0:32 offset1:36
	s_waitcnt lgkmcnt(1)
	v_mfma_f32_16x16x32_bf16 v[44:47], v[48:51], v[60:63], v[44:47]
	v_mul_f32_e64 v50, v38, v0
	v_mul_f32_e64 v51, v39, v0
	v_mul_f32_e32 v48, v36, v0
	v_mul_f32_e32 v49, v37, v0
	s_waitcnt lgkmcnt(0)
	s_nop 0
	v_mfma_f32_16x16x32_bf16 v[48:51], v[52:55], v[56:59], v[48:51]
	ds_read2_b64 v[52:55], v3 offset0:40 offset1:44
	v_add_u32_e32 v3, 0x5800, v1
	ds_read2_b64 v[64:67], v3 offset0:64 offset1:68
	s_waitcnt lgkmcnt(1)
	v_mfma_f32_16x16x32_bf16 v[48:51], v[52:55], v[60:63], v[48:51]
	v_mul_f32_e64 v54, v34, v0
	v_mul_f32_e64 v55, v35, v0
	v_mul_f32_e32 v52, v32, v0
	v_mul_f32_e32 v53, v33, v0
	s_waitcnt lgkmcnt(0)
	s_nop 0
	v_mfma_f32_16x16x32_bf16 v[52:55], v[64:67], v[56:59], v[52:55]
	ds_read2_b64 v[64:67], v3 offset0:72 offset1:76
	s_waitcnt lgkmcnt(0)
	v_mfma_f32_16x16x32_bf16 v[52:55], v[64:67], v[60:63], v[52:55]
	v_mul_f32_e64 v66, v30, v0
	v_mul_f32_e64 v67, v31, v0
	v_mul_f32_e32 v64, v28, v0
	v_mul_f32_e32 v65, v29, v0
	v_add_u32_e32 v0, 0x6000, v1
	ds_read2_b64 v[68:71], v0 offset0:96 offset1:100
	s_waitcnt lgkmcnt(0)
	v_mfma_f32_16x16x32_bf16 v[56:59], v[68:71], v[56:59], v[64:67]
	s_nop 2
	ds_read2_b64 v[64:67], v0 offset0:104 offset1:108
	s_waitcnt vmcnt(0)
	v_mov_b64_e32 v[0:1], v[146:147]
	v_mov_b64_e32 v[68:69], v[144:145]
	s_waitcnt lgkmcnt(0)
	v_mfma_f32_16x16x32_bf16 v[56:59], v[64:67], v[60:63], v[56:59]
	v_mov_b64_e32 v[70:71], v[142:143]
